# v17 + ssm chunk scan: 8 LDS reads of each unrolled block issued up front with counted lgkmcnt
# speedup vs baseline: 1.0119x; 1.0119x over previous
.LBB0_117:
	ds_read2st64_b32 v[20:21], v12 offset1:1
	ds_read2st64_b32 v[22:23], v12 offset0:2 offset1:3
	ds_read2st64_b32 v[24:25], v12 offset0:4 offset1:5
	ds_read2st64_b32 v[26:27], v12 offset0:6 offset1:7
	ds_read2st64_b32 v[28:29], v12 offset0:8 offset1:9
	ds_read2st64_b32 v[30:31], v12 offset0:10 offset1:11
	ds_read2st64_b32 v[32:33], v12 offset0:12 offset1:13
	ds_read2st64_b32 v[34:35], v12 offset0:14 offset1:15
	v_bfe_u32 v10, v8, 16, 1
	v_add3_u32 v13, v8, v10, s36
	v_lshl_add_u64 v[10:11], v[4:5], 0, s[10:11]
	v_add_co_u32_e32 v14, vcc, 0x13e00000, v10
	v_pk_mul_f32 v[16:17], v[6:7], v[8:9] op_sel:[0,1]
	s_nop 0
	v_addc_co_u32_e32 v15, vcc, 0, v11, vcc
	global_store_short_d16_hi v[14:15], v13, off
	v_bfe_u32 v13, v9, 16, 1
	v_add3_u32 v13, v9, v13, s36
	global_store_short_d16_hi v[14:15], v13, off offset:128
	v_pk_fma_f32 v[18:19], v[2:3], v[8:9], v[16:17] neg_lo:[0,0,1] neg_hi:[0,0,1]
	v_pk_fma_f32 v[8:9], v[2:3], v[8:9], v[16:17] op_sel_hi:[1,0,1]
	s_mov_b32 s5, 0x13e08000
	v_mov_b32_e32 v19, v9
	s_waitcnt lgkmcnt(7)
	v_pk_add_f32 v[8:9], v[18:19], v[20:21]
	v_add_co_u32_e32 v14, vcc, s37, v10
	v_bfe_u32 v13, v8, 16, 1
	v_add3_u32 v13, v8, v13, s36
	v_addc_co_u32_e32 v15, vcc, 0, v11, vcc
	global_store_short_d16_hi v[14:15], v13, off
	v_bfe_u32 v13, v9, 16, 1
	v_add3_u32 v13, v9, v13, s36
	global_store_short_d16_hi v[14:15], v13, off offset:128
	v_pk_mul_f32 v[16:17], v[6:7], v[8:9] op_sel:[0,1]
	s_add_u32 s10, s10, 0x20000
	v_pk_fma_f32 v[18:19], v[2:3], v[8:9], v[16:17] neg_lo:[0,0,1] neg_hi:[0,0,1]
	v_pk_fma_f32 v[8:9], v[2:3], v[8:9], v[16:17] op_sel_hi:[1,0,1]
	s_addc_u32 s11, s11, 0
	v_mov_b32_e32 v19, v9
	s_waitcnt lgkmcnt(6)
	v_pk_add_f32 v[8:9], v[18:19], v[22:23]
	v_add_co_u32_e32 v14, vcc, s5, v10
	v_bfe_u32 v13, v8, 16, 1
	v_add3_u32 v13, v8, v13, s36
	v_addc_co_u32_e32 v15, vcc, 0, v11, vcc
	global_store_short_d16_hi v[14:15], v13, off
	v_bfe_u32 v13, v9, 16, 1
	v_add3_u32 v13, v9, v13, s36
	global_store_short_d16_hi v[14:15], v13, off offset:128
	v_pk_mul_f32 v[16:17], v[6:7], v[8:9] op_sel:[0,1]
	s_mov_b32 s5, 0x13e0c000
	v_pk_fma_f32 v[18:19], v[2:3], v[8:9], v[16:17] neg_lo:[0,0,1] neg_hi:[0,0,1]
	v_pk_fma_f32 v[8:9], v[2:3], v[8:9], v[16:17] op_sel_hi:[1,0,1]
	s_cmp_lg_u32 s10, 0x200000
	v_mov_b32_e32 v19, v9
	s_waitcnt lgkmcnt(5)
	v_pk_add_f32 v[8:9], v[18:19], v[24:25]
	v_add_co_u32_e32 v14, vcc, s5, v10
	v_bfe_u32 v13, v8, 16, 1
	v_add3_u32 v13, v8, v13, s36
	v_addc_co_u32_e32 v15, vcc, 0, v11, vcc
	global_store_short_d16_hi v[14:15], v13, off
	v_bfe_u32 v13, v9, 16, 1
	v_add3_u32 v13, v9, v13, s36
	global_store_short_d16_hi v[14:15], v13, off offset:128
	v_pk_mul_f32 v[16:17], v[6:7], v[8:9] op_sel:[0,1]
	s_mov_b32 s5, 0x13e10000
	v_pk_fma_f32 v[18:19], v[2:3], v[8:9], v[16:17] neg_lo:[0,0,1] neg_hi:[0,0,1]
	v_pk_fma_f32 v[8:9], v[2:3], v[8:9], v[16:17] op_sel_hi:[1,0,1]
	s_nop 0
	v_mov_b32_e32 v19, v9
	s_waitcnt lgkmcnt(4)
	v_pk_add_f32 v[8:9], v[18:19], v[26:27]
	v_add_co_u32_e32 v14, vcc, s5, v10
	v_bfe_u32 v13, v8, 16, 1
	v_add3_u32 v13, v8, v13, s36
	v_addc_co_u32_e32 v15, vcc, 0, v11, vcc
	global_store_short_d16_hi v[14:15], v13, off
	v_bfe_u32 v13, v9, 16, 1
	v_add3_u32 v13, v9, v13, s36
	global_store_short_d16_hi v[14:15], v13, off offset:128
	v_pk_mul_f32 v[16:17], v[6:7], v[8:9] op_sel:[0,1]
	s_mov_b32 s5, 0x13e14000
	v_pk_fma_f32 v[18:19], v[2:3], v[8:9], v[16:17] neg_lo:[0,0,1] neg_hi:[0,0,1]
	v_pk_fma_f32 v[8:9], v[2:3], v[8:9], v[16:17] op_sel_hi:[1,0,1]
	s_nop 0
	v_mov_b32_e32 v19, v9
	s_waitcnt lgkmcnt(3)
	v_pk_add_f32 v[8:9], v[18:19], v[28:29]
	v_add_co_u32_e32 v14, vcc, s5, v10
	v_bfe_u32 v13, v8, 16, 1
	v_add3_u32 v13, v8, v13, s36
	v_addc_co_u32_e32 v15, vcc, 0, v11, vcc
	global_store_short_d16_hi v[14:15], v13, off
	v_bfe_u32 v13, v9, 16, 1
	v_add3_u32 v13, v9, v13, s36
	global_store_short_d16_hi v[14:15], v13, off offset:128
	v_pk_mul_f32 v[16:17], v[6:7], v[8:9] op_sel:[0,1]
	s_mov_b32 s5, 0x13e18000
	v_pk_fma_f32 v[18:19], v[2:3], v[8:9], v[16:17] neg_lo:[0,0,1] neg_hi:[0,0,1]
	v_pk_fma_f32 v[8:9], v[2:3], v[8:9], v[16:17] op_sel_hi:[1,0,1]
	s_nop 0
	v_mov_b32_e32 v19, v9
	s_waitcnt lgkmcnt(2)
	v_pk_add_f32 v[8:9], v[18:19], v[30:31]
	v_add_co_u32_e32 v14, vcc, s5, v10
	v_bfe_u32 v13, v8, 16, 1
	v_add3_u32 v13, v8, v13, s36
	v_addc_co_u32_e32 v15, vcc, 0, v11, vcc
	global_store_short_d16_hi v[14:15], v13, off
	v_bfe_u32 v13, v9, 16, 1
	v_add3_u32 v13, v9, v13, s36
	global_store_short_d16_hi v[14:15], v13, off offset:128
	v_pk_mul_f32 v[16:17], v[6:7], v[8:9] op_sel:[0,1]
	s_mov_b32 s5, 0x13e1c000
	v_pk_fma_f32 v[18:19], v[2:3], v[8:9], v[16:17] neg_lo:[0,0,1] neg_hi:[0,0,1]
	v_pk_fma_f32 v[8:9], v[2:3], v[8:9], v[16:17] op_sel_hi:[1,0,1]
	v_add_co_u32_e32 v10, vcc, s5, v10
	v_mov_b32_e32 v19, v9
	s_waitcnt lgkmcnt(1)
	v_pk_add_f32 v[8:9], v[18:19], v[32:33]
	v_addc_co_u32_e32 v11, vcc, 0, v11, vcc
	v_bfe_u32 v13, v8, 16, 1
	v_add3_u32 v13, v8, v13, s36
	global_store_short_d16_hi v[10:11], v13, off
	v_bfe_u32 v13, v9, 16, 1
	v_add3_u32 v13, v9, v13, s36
	global_store_short_d16_hi v[10:11], v13, off offset:128
	v_pk_mul_f32 v[14:15], v[6:7], v[8:9] op_sel:[0,1]
	v_add_u32_e32 v12, 0x1000, v12
	v_pk_fma_f32 v[16:17], v[2:3], v[8:9], v[14:15] neg_lo:[0,0,1] neg_hi:[0,0,1]
	v_pk_fma_f32 v[8:9], v[2:3], v[8:9], v[14:15] op_sel_hi:[1,0,1]
	s_nop 0
	v_mov_b32_e32 v17, v9
	s_waitcnt lgkmcnt(0)
	v_pk_add_f32 v[8:9], v[16:17], v[34:35]
	s_cbranch_scc1 .LBB0_117
	v_mov_b64_e32 v[2:3], s[8:9]
